# grid barrier: waiting blocks poll the top-level generation word directly instead of their XCD's generation word (one notification hop instead of two)
# baseline (speedup 1.0000x reference)
.LBB0_278:
	global_atomic_add v3, v[144:145], v175, off sc0
	v_cvt_f32_u32_e32 v1, v2
	v_sub_u32_e32 v4, 0, v2
	v_rcp_iflag_f32_e32 v1, v1
	s_nop 0
	v_mul_f32_e32 v1, 0x4f7ffffe, v1
	v_cvt_u32_f32_e32 v1, v1
	v_mul_lo_u32 v4, v4, v1
	v_mul_hi_u32 v4, v1, v4
	v_add_u32_e32 v1, v1, v4
	s_waitcnt vmcnt(0)
	v_mul_hi_u32 v1, v3, v1
	v_mul_lo_u32 v4, v1, v2
	v_sub_u32_e32 v4, v3, v4
	v_add_u32_e32 v5, 1, v1
	v_cmp_ge_u32_e32 vcc, v4, v2
	v_add_u32_e32 v3, 1, v3
	s_nop 0
	v_cndmask_b32_e32 v1, v1, v5, vcc
	v_sub_u32_e32 v5, v4, v2
	v_cndmask_b32_e32 v4, v4, v5, vcc
	v_add_u32_e32 v5, 1, v1
	v_cmp_ge_u32_e32 vcc, v4, v2
	s_nop 1
	v_cndmask_b32_e32 v1, v1, v5, vcc
	v_mul_lo_u32 v4, v2, v1
	v_add_u32_e32 v2, v4, v2
	v_cmp_ne_u32_e32 vcc, v3, v2
	s_and_saveexec_b64 s[4:5], vcc
	s_xor_b64 s[4:5], exec, s[4:5]
	s_cbranch_execz .LBB0_292
	s_waitcnt lgkmcnt(0)
	v_mov_b32_e32 v0, 0x3300
	global_load_dword v0, v0, s[78:79] sc1
	s_waitcnt vmcnt(0)
	v_cmp_eq_u32_e32 vcc, v0, v1
	s_and_saveexec_b64 s[6:7], vcc
	s_cbranch_execz .LBB0_291
	s_mov_b32 s18, 1
	s_mov_b64 s[8:9], 0
	s_branch .LBB0_282

.LBB0_286:
	v_mov_b32_e32 v0, 0x3300
	global_load_dword v0, v0, s[78:79] sc1
	s_add_i32 s18, s18, 1
	s_mov_b64 s[14:15], -1
	s_waitcnt vmcnt(0)
	v_cmp_ne_u32_e32 vcc, v0, v1
	s_orn2_b64 s[12:13], vcc, exec
	s_branch .LBB0_281

.LBB0_427:
	global_atomic_add v3, v[144:145], v175, off sc0
	v_cvt_f32_u32_e32 v1, v2
	v_sub_u32_e32 v4, 0, v2
	v_rcp_iflag_f32_e32 v1, v1
	s_nop 0
	v_mul_f32_e32 v1, 0x4f7ffffe, v1
	v_cvt_u32_f32_e32 v1, v1
	v_mul_lo_u32 v4, v4, v1
	v_mul_hi_u32 v4, v1, v4
	v_add_u32_e32 v1, v1, v4
	s_waitcnt vmcnt(0)
	v_mul_hi_u32 v1, v3, v1
	v_mul_lo_u32 v4, v1, v2
	v_sub_u32_e32 v4, v3, v4
	v_add_u32_e32 v5, 1, v1
	v_cmp_ge_u32_e32 vcc, v4, v2
	v_add_u32_e32 v3, 1, v3
	s_nop 0
	v_cndmask_b32_e32 v1, v1, v5, vcc
	v_sub_u32_e32 v5, v4, v2
	v_cndmask_b32_e32 v4, v4, v5, vcc
	v_add_u32_e32 v5, 1, v1
	v_cmp_ge_u32_e32 vcc, v4, v2
	s_nop 1
	v_cndmask_b32_e32 v1, v1, v5, vcc
	v_mul_lo_u32 v4, v2, v1
	v_add_u32_e32 v2, v4, v2
	v_cmp_ne_u32_e32 vcc, v3, v2
	s_and_saveexec_b64 s[2:3], vcc
	s_xor_b64 s[2:3], exec, s[2:3]
	s_cbranch_execz .LBB0_441
	s_waitcnt lgkmcnt(0)
	v_mov_b32_e32 v0, 0x3300
	global_load_dword v0, v0, s[78:79] sc1
	s_waitcnt vmcnt(0)
	v_cmp_eq_u32_e32 vcc, v0, v1
	s_and_saveexec_b64 s[4:5], vcc
	s_cbranch_execz .LBB0_440
	s_mov_b32 s16, 1
	s_mov_b64 s[6:7], 0
	s_branch .LBB0_431

.LBB0_435:
	v_mov_b32_e32 v0, 0x3300
	global_load_dword v0, v0, s[78:79] sc1
	s_add_i32 s16, s16, 1
	s_mov_b64 s[12:13], -1
	s_waitcnt vmcnt(0)
	v_cmp_ne_u32_e32 vcc, v0, v1
	s_orn2_b64 s[10:11], vcc, exec
	s_branch .LBB0_430
